# fewer instructions per byte: LN prompt-row touch-prefetch uses 16 dwordx4 loads instead of 32 dwordx2, on top of v86
# speedup vs baseline: 1.0026x; 1.0026x over previous
.LBB0_155:
	v_lshl_add_u64 v[2:3], s[66:67], 0, v[36:37]
	s_mov_b64 s[0:1], 0x2600000
	v_lshl_add_u64 v[10:11], v[2:3], 0, s[0:1]
	v_add_co_u32_e32 v2, vcc, 0x2600000, v2
	s_mov_b64 s[0:1], 0xe00
	s_nop 0
	v_addc_co_u32_e32 v3, vcc, 0, v3, vcc
	v_lshl_add_u64 v[220:221], s[66:67], 0, v[14:15]
	v_add_co_u32_e32 v220, vcc, 0x2600000, v220
	s_nop 0
	v_addc_co_u32_e32 v221, vcc, 0, v221, vcc
	global_load_dwordx4 v[224:227], v[220:221], off
	global_load_dwordx4 v[224:227], v[220:221], off offset:1024
	global_load_dwordx4 v[224:227], v[220:221], off offset:2048
	global_load_dwordx4 v[224:227], v[220:221], off offset:3072
	v_lshl_add_u64 v[220:221], v[220:221], 0, s[70:71]
	global_load_dwordx4 v[224:227], v[220:221], off
	global_load_dwordx4 v[224:227], v[220:221], off offset:1024
	global_load_dwordx4 v[224:227], v[220:221], off offset:2048
	global_load_dwordx4 v[224:227], v[220:221], off offset:3072
	v_lshl_add_u64 v[220:221], v[220:221], 0, s[70:71]
	global_load_dwordx4 v[224:227], v[220:221], off
	global_load_dwordx4 v[224:227], v[220:221], off offset:1024
	global_load_dwordx4 v[224:227], v[220:221], off offset:2048
	global_load_dwordx4 v[224:227], v[220:221], off offset:3072
	v_lshl_add_u64 v[220:221], v[220:221], 0, s[70:71]
	global_load_dwordx4 v[224:227], v[220:221], off
	global_load_dwordx4 v[224:227], v[220:221], off offset:1024
	global_load_dwordx4 v[224:227], v[220:221], off offset:2048
	global_load_dwordx4 v[224:227], v[220:221], off offset:3072
	global_load_dwordx2 v[4:5], v[2:3], off
	global_load_dwordx2 v[6:7], v[10:11], off offset:512
	s_nop 0
	global_load_dwordx2 v[2:3], v[10:11], off offset:1024
	global_load_dwordx2 v[8:9], v[10:11], off offset:1536
	s_andn2_b64 vcc, exec, s[22:23]
	s_waitcnt vmcnt(0)
	v_lshlrev_b32_e32 v116, 16, v4
	v_lshlrev_b32_e32 v117, 16, v6
	v_and_b32_e32 v179, 0xffff0000, v6
	v_lshlrev_b32_e32 v112, 16, v8
	v_and_b32_e32 v113, 0xffff0000, v8
	v_lshlrev_b32_e32 v110, 16, v9
	v_and_b32_e32 v111, 0xffff0000, v9
	global_load_dwordx2 v[8:9], v[10:11], off offset:2048
	v_and_b32_e32 v178, 0xffff0000, v4
	v_lshlrev_b32_e32 v162, 16, v5
	v_lshlrev_b32_e32 v163, 16, v7
	v_and_b32_e32 v181, 0xffff0000, v7
	v_and_b32_e32 v180, 0xffff0000, v5
	v_pk_add_f32 v[4:5], v[116:117], v[178:179]
	v_pk_add_f32 v[6:7], v[162:163], v[180:181]
	v_lshlrev_b32_e32 v157, 16, v3
	v_lshlrev_b32_e32 v156, 16, v2
	v_and_b32_e32 v147, 0xffff0000, v3
	v_and_b32_e32 v146, 0xffff0000, v2
	v_pk_add_f32 v[4:5], v[4:5], v[6:7]
	v_pk_add_f32 v[2:3], v[156:157], v[146:147]
	v_add_f32_e32 v0, 0, v4
	v_pk_add_f32 v[2:3], v[2:3], v[2:3] op_sel:[0,1] op_sel_hi:[1,0]
	v_add_f32_e32 v88, v0, v5
	v_add_f32_e32 v86, v112, v113
	v_add_f32_e32 v84, v110, v111
	s_waitcnt vmcnt(0)
	v_lshlrev_b32_e32 v89, 16, v8
	v_and_b32_e32 v83, 0xffff0000, v8
	v_lshlrev_b32_e32 v87, 16, v9
	v_and_b32_e32 v85, 0xffff0000, v9
	global_load_dwordx2 v[8:9], v[10:11], off offset:2560
	global_load_dwordx2 v[12:13], v[10:11], off offset:3072
	v_mov_b32_e32 v3, v83
	v_pk_add_f32 v[2:3], v[88:89], v[2:3]
	v_pk_add_f32 v[4:5], v[86:87], v[84:85]
	s_waitcnt vmcnt(1)
	v_lshlrev_b32_e32 v141, 16, v9
	s_waitcnt vmcnt(0)
	v_lshlrev_b32_e32 v58, 16, v12
	v_and_b32_e32 v59, 0xffff0000, v12
	v_lshlrev_b32_e32 v60, 16, v13
	v_and_b32_e32 v61, 0xffff0000, v13
	v_lshl_add_u64 v[12:13], v[10:11], 0, s[0:1]
	global_load_dwordx2 v[10:11], v[10:11], off offset:3584
	v_lshl_add_u64 v[38:39], v[12:13], 0, s[82:83]
	v_lshl_add_u64 v[50:51], v[38:39], 0, s[0:1]
	v_lshl_add_u64 v[50:51], v[50:51], 0, s[82:83]
	v_lshl_add_u64 v[68:69], v[50:51], 0, s[0:1]
	v_lshl_add_u64 v[70:71], v[68:69], 0, s[82:83]
	v_lshlrev_b32_e32 v140, 16, v8
	v_and_b32_e32 v143, 0xffff0000, v9
	v_and_b32_e32 v142, 0xffff0000, v8
	v_pk_add_f32 v[2:3], v[2:3], v[4:5]
	v_pk_add_f32 v[4:5], v[140:141], v[142:143]
	v_pk_add_f32 v[2:3], v[2:3], v[2:3] op_sel:[0,1] op_sel_hi:[1,0]
	v_pk_add_f32 v[4:5], v[4:5], v[4:5] op_sel:[0,1] op_sel_hi:[1,0]
	v_add_f32_e32 v46, v58, v59
	v_add_f32_e32 v44, v60, v61
	s_waitcnt vmcnt(0)
	v_lshlrev_b32_e32 v42, 16, v10
	v_and_b32_e32 v43, 0xffff0000, v10
	v_lshlrev_b32_e32 v47, 16, v11
	v_and_b32_e32 v45, 0xffff0000, v11
	global_load_dwordx2 v[12:13], v[38:39], off
	global_load_dwordx2 v[124:125], v[38:39], off offset:512
	global_load_dwordx2 v[10:11], v[38:39], off offset:1024
	global_load_dwordx2 v[40:41], v[38:39], off offset:1536
	v_mov_b32_e32 v3, v42
	v_mov_b32_e32 v5, v43
	v_pk_add_f32 v[2:3], v[2:3], v[4:5]
	v_pk_add_f32 v[4:5], v[46:47], v[44:45]
	s_waitcnt vmcnt(3)
	v_lshlrev_b32_e32 v200, 16, v12
	v_pk_add_f32 v[2:3], v[2:3], v[4:5]
	s_waitcnt vmcnt(2)
	v_lshlrev_b32_e32 v201, 16, v124
	s_waitcnt vmcnt(0)
	v_lshlrev_b32_e32 v118, 16, v40
	v_and_b32_e32 v119, 0xffff0000, v40
	v_lshlrev_b32_e32 v114, 16, v41
	v_and_b32_e32 v115, 0xffff0000, v41
	global_load_dwordx2 v[40:41], v[38:39], off offset:2048
	v_add_f32_e32 v0, v2, v3
	v_and_b32_e32 v189, 0xffff0000, v124
	v_and_b32_e32 v188, 0xffff0000, v12
	v_add_f32_dpp v0, v0, v0 quad_perm:[1,0,3,2] row_mask:0xf bank_mask:0xf bound_ctrl:1
	v_lshlrev_b32_e32 v151, 16, v125
	v_lshlrev_b32_e32 v150, 16, v13
	v_add_f32_dpp v0, v0, v0 quad_perm:[2,3,0,1] row_mask:0xf bank_mask:0xf bound_ctrl:1
	v_and_b32_e32 v177, 0xffff0000, v125
	v_and_b32_e32 v176, 0xffff0000, v13
	v_add_f32_dpp v0, v0, v0 row_half_mirror row_mask:0xf bank_mask:0xf bound_ctrl:1
	v_pk_add_f32 v[4:5], v[150:151], v[176:177]
	v_lshlrev_b32_e32 v155, 16, v11
	v_add_f32_dpp v0, v0, v0 row_ror:8 row_mask:0xf bank_mask:0xf bound_ctrl:1
	v_lshlrev_b32_e32 v154, 16, v10
	v_readlane_b32 s2, v0, 16
	v_readlane_b32 s3, v0, 48
	v_readlane_b32 s0, v0, 0
	v_readlane_b32 s1, v0, 32
	v_mov_b32_e32 v2, s2
	v_mov_b32_e32 v3, s3
	v_pk_add_f32 v[2:3], s[0:1], v[2:3]
	v_and_b32_e32 v153, 0xffff0000, v11
	v_add_f32_e32 v0, v2, v3
	v_pk_add_f32 v[2:3], v[200:201], v[188:189]
	v_and_b32_e32 v152, 0xffff0000, v10
	v_pk_add_f32 v[2:3], v[2:3], v[4:5]
	v_add_f32_e32 v80, v118, v119
	v_add_f32_e32 v2, 0, v2
	v_add_f32_e32 v104, v2, v3
	v_pk_add_f32 v[2:3], v[154:155], v[152:153]
	v_add_f32_e32 v78, v114, v115
	v_pk_add_f32 v[2:3], v[2:3], v[2:3] op_sel:[0,1] op_sel_hi:[1,0]
	v_fmac_f32_e32 v146, 0xba000000, v0
	v_fmac_f32_e32 v156, 0xba000000, v0
	v_fmac_f32_e32 v147, 0xba000000, v0
	v_fmac_f32_e32 v157, 0xba000000, v0
	v_mov_b32_e32 v6, v156
	v_mov_b32_e32 v7, v146
	v_pk_mul_f32 v[6:7], v[6:7], v[6:7]
	v_mov_b32_e32 v8, v157
	v_mov_b32_e32 v9, v147
	v_fmac_f32_e32 v113, 0xba000000, v0
	v_fmac_f32_e32 v112, 0xba000000, v0
	v_pk_fma_f32 v[6:7], v[8:9], v[8:9], v[6:7]
	v_fmac_f32_e32 v111, 0xba000000, v0
	v_fmac_f32_e32 v110, 0xba000000, v0
	v_pk_mul_f32 v[8:9], v[112:113], v[112:113]
	v_fmac_f32_e32 v178, 0xba000000, v0
	v_fmac_f32_e32 v116, 0xba000000, v0
	v_fmac_f32_e32 v117, 0xba000000, v0
	v_pk_fma_f32 v[8:9], v[110:111], v[110:111], v[8:9]
	v_fmac_f32_e32 v180, 0xba000000, v0
	v_fmac_f32_e32 v162, 0xba000000, v0
	v_mov_b32_e32 v10, v116
	v_mov_b32_e32 v11, v178
	v_fmac_f32_e32 v163, 0xba000000, v0
	v_fmac_f32_e32 v179, 0xba000000, v0
	v_mov_b32_e32 v178, v117
	v_fmac_f32_e32 v89, 0xba000000, v0
	v_fmac_f32_e32 v142, 0xba000000, v0
	v_fmac_f32_e32 v140, 0xba000000, v0
	v_mov_b32_e32 v12, v162
	v_mov_b32_e32 v13, v180
	v_fmac_f32_e32 v181, 0xba000000, v0
	v_mov_b32_e32 v180, v163
	v_fmac_f32_e32 v87, 0xba000000, v0
	v_fmac_f32_e32 v83, 0xba000000, v0
	v_mov_b32_e32 v82, v89
	v_fmac_f32_e32 v143, 0xba000000, v0
	v_fmac_f32_e32 v141, 0xba000000, v0
	v_fmac_f32_e32 v85, 0xba000000, v0
	v_mov_b32_e32 v84, v87
	v_fmac_f32_e32 v61, 0xba000000, v0
	v_fmac_f32_e32 v60, 0xba000000, v0
	v_fmac_f32_e32 v59, 0xba000000, v0
	v_fmac_f32_e32 v58, 0xba000000, v0
	v_fmac_f32_e32 v45, 0xba000000, v0
	v_fmac_f32_e32 v47, 0xba000000, v0
	v_fmac_f32_e32 v43, 0xba000000, v0
	s_waitcnt vmcnt(0)
	v_lshlrev_b32_e32 v105, 16, v40
	v_and_b32_e32 v91, 0xffff0000, v40
	v_lshlrev_b32_e32 v81, 16, v41
	v_and_b32_e32 v79, 0xffff0000, v41
	global_load_dwordx2 v[130:131], v[38:39], off offset:2560
	global_load_dwordx2 v[40:41], v[38:39], off offset:3072
	v_mov_b32_e32 v3, v91
	global_load_dwordx2 v[38:39], v[38:39], off offset:3584
	s_nop 0
	global_load_dwordx2 v[134:135], v[50:51], off
	global_load_dwordx2 v[136:137], v[50:51], off offset:512
	global_load_dwordx2 v[132:133], v[50:51], off offset:1024
	global_load_dwordx2 v[52:53], v[50:51], off offset:1536
	v_pk_add_f32 v[2:3], v[104:105], v[2:3]
	v_pk_add_f32 v[4:5], v[80:81], v[78:79]
	v_fmac_f32_e32 v42, 0xba000000, v0
	v_pk_add_f32 v[2:3], v[2:3], v[4:5]
	v_mov_b32_e32 v44, v47
	v_pk_add_f32 v[2:3], v[2:3], v[2:3] op_sel:[0,1] op_sel_hi:[1,0]
	s_waitcnt vmcnt(6)
	v_lshlrev_b32_e32 v127, 16, v131
	v_lshlrev_b32_e32 v126, 16, v130
	v_and_b32_e32 v125, 0xffff0000, v131
	v_and_b32_e32 v124, 0xffff0000, v130
	s_waitcnt vmcnt(0)
	v_lshlrev_b32_e32 v120, 16, v52
	v_and_b32_e32 v121, 0xffff0000, v52
	v_lshlrev_b32_e32 v122, 16, v53
	v_and_b32_e32 v123, 0xffff0000, v53
	global_load_dwordx2 v[52:53], v[50:51], off offset:2048
	v_pk_add_f32 v[4:5], v[126:127], v[124:125]
	v_lshlrev_b32_e32 v62, 16, v40
	v_and_b32_e32 v63, 0xffff0000, v40
	v_lshlrev_b32_e32 v56, 16, v41
	v_and_b32_e32 v57, 0xffff0000, v41
	v_lshlrev_b32_e32 v48, 16, v38
	v_and_b32_e32 v49, 0xffff0000, v38
	v_pk_add_f32 v[4:5], v[4:5], v[4:5] op_sel:[0,1] op_sel_hi:[1,0]
	v_lshlrev_b32_e32 v41, 16, v39
	v_and_b32_e32 v39, 0xffff0000, v39
	v_add_f32_e32 v40, v62, v63
	v_add_f32_e32 v38, v56, v57
	v_mov_b32_e32 v3, v48
	v_mov_b32_e32 v5, v49
	v_pk_add_f32 v[2:3], v[2:3], v[4:5]
	v_pk_add_f32 v[4:5], v[40:41], v[38:39]
	v_lshlrev_b32_e32 v195, 16, v136
	v_pk_add_f32 v[2:3], v[2:3], v[4:5]
	v_lshlrev_b32_e32 v194, 16, v134
	v_add_f32_e32 v2, v2, v3
	v_and_b32_e32 v183, 0xffff0000, v136
	v_and_b32_e32 v182, 0xffff0000, v134
	v_add_f32_dpp v2, v2, v2 quad_perm:[1,0,3,2] row_mask:0xf bank_mask:0xf bound_ctrl:1
	v_lshlrev_b32_e32 v187, 16, v137
	v_lshlrev_b32_e32 v186, 16, v135
	v_add_f32_dpp v2, v2, v2 quad_perm:[2,3,0,1] row_mask:0xf bank_mask:0xf bound_ctrl:1
	v_and_b32_e32 v185, 0xffff0000, v137
	v_and_b32_e32 v184, 0xffff0000, v135
	v_add_f32_dpp v2, v2, v2 row_half_mirror row_mask:0xf bank_mask:0xf bound_ctrl:1
	v_pk_add_f32 v[4:5], v[186:187], v[184:185]
	v_lshlrev_b32_e32 v169, 16, v133
	v_add_f32_dpp v2, v2, v2 row_ror:8 row_mask:0xf bank_mask:0xf bound_ctrl:1
	v_lshlrev_b32_e32 v168, 16, v132
	v_readlane_b32 s2, v2, 16
	v_readlane_b32 s3, v2, 48
	v_readlane_b32 s0, v2, 0
	v_readlane_b32 s1, v2, 32
	v_mov_b32_e32 v2, s2
	v_mov_b32_e32 v3, s3
	v_pk_add_f32 v[2:3], s[0:1], v[2:3]
	v_and_b32_e32 v167, 0xffff0000, v133
	v_add_f32_e32 v38, v2, v3
	v_pk_add_f32 v[2:3], v[194:195], v[182:183]
	v_and_b32_e32 v166, 0xffff0000, v132
	v_pk_add_f32 v[2:3], v[2:3], v[4:5]
	v_add_f32_e32 v96, v120, v121
	v_add_f32_e32 v2, 0, v2
	v_add_f32_e32 v98, v2, v3
	v_pk_add_f32 v[2:3], v[168:169], v[166:167]
	v_add_f32_e32 v94, v122, v123
	v_pk_add_f32 v[2:3], v[2:3], v[2:3] op_sel:[0,1] op_sel_hi:[1,0]
	v_fmac_f32_e32 v188, 0xba000000, v38
	v_fmac_f32_e32 v200, 0xba000000, v38
	v_fmac_f32_e32 v189, 0xba000000, v38
	v_fmac_f32_e32 v201, 0xba000000, v38
	v_fmac_f32_e32 v176, 0xba000000, v38
	v_fmac_f32_e32 v150, 0xba000000, v38
	v_fmac_f32_e32 v151, 0xba000000, v38
	v_fmac_f32_e32 v152, 0xba000000, v38
	v_fmac_f32_e32 v154, 0xba000000, v38
	v_fmac_f32_e32 v177, 0xba000000, v38
	v_fmac_f32_e32 v153, 0xba000000, v38
	v_fmac_f32_e32 v155, 0xba000000, v38
	v_fmac_f32_e32 v119, 0xba000000, v38
	v_fmac_f32_e32 v118, 0xba000000, v38
	v_fmac_f32_e32 v105, 0xba000000, v38
	v_fmac_f32_e32 v115, 0xba000000, v38
	v_fmac_f32_e32 v114, 0xba000000, v38
	v_fmac_f32_e32 v81, 0xba000000, v38
	v_fmac_f32_e32 v91, 0xba000000, v38
	v_mov_b32_e32 v90, v105
	v_fmac_f32_e32 v124, 0xba000000, v38
	v_fmac_f32_e32 v126, 0xba000000, v38
	v_fmac_f32_e32 v79, 0xba000000, v38
	v_mov_b32_e32 v78, v81
	v_fmac_f32_e32 v125, 0xba000000, v38
	v_fmac_f32_e32 v127, 0xba000000, v38
	v_fmac_f32_e32 v63, 0xba000000, v38
	v_fmac_f32_e32 v62, 0xba000000, v38
	s_waitcnt vmcnt(0)
	v_lshlrev_b32_e32 v99, 16, v52
	v_and_b32_e32 v93, 0xffff0000, v52
	v_lshlrev_b32_e32 v97, 16, v53
	v_and_b32_e32 v95, 0xffff0000, v53
	global_load_dwordx2 v[148:149], v[50:51], off offset:2560
	global_load_dwordx2 v[52:53], v[50:51], off offset:3072
	v_mov_b32_e32 v3, v93
	v_pk_add_f32 v[2:3], v[98:99], v[2:3]
	v_pk_add_f32 v[4:5], v[96:97], v[94:95]
	v_fmac_f32_e32 v57, 0xba000000, v38
	v_pk_add_f32 v[2:3], v[2:3], v[4:5]
	v_fmac_f32_e32 v56, 0xba000000, v38
	v_pk_add_f32 v[2:3], v[2:3], v[2:3] op_sel:[0,1] op_sel_hi:[1,0]
	v_fmac_f32_e32 v41, 0xba000000, v38
	v_fmac_f32_e32 v49, 0xba000000, v38
	v_fmac_f32_e32 v48, 0xba000000, v38
	v_fmac_f32_e32 v39, 0xba000000, v38
	v_mov_b32_e32 v38, v41
	s_waitcnt vmcnt(1)
	v_lshlrev_b32_e32 v137, 16, v149
	s_waitcnt vmcnt(0)
	v_lshlrev_b32_e32 v64, 16, v52
	v_and_b32_e32 v65, 0xffff0000, v52
	v_lshlrev_b32_e32 v66, 16, v53
	v_and_b32_e32 v67, 0xffff0000, v53
	global_load_dwordx2 v[52:53], v[50:51], off offset:3584
	global_load_dwordx2 v[160:161], v[70:71], off
	global_load_dwordx2 v[164:165], v[70:71], off offset:512
	global_load_dwordx2 v[158:159], v[70:71], off offset:1024
	global_load_dwordx2 v[68:69], v[70:71], off offset:1536
	v_lshlrev_b32_e32 v136, 16, v148
	v_and_b32_e32 v135, 0xffff0000, v149
	v_and_b32_e32 v134, 0xffff0000, v148
	v_pk_add_f32 v[4:5], v[136:137], v[134:135]
	v_add_f32_e32 v54, v64, v65
	v_pk_add_f32 v[4:5], v[4:5], v[4:5] op_sel:[0,1] op_sel_hi:[1,0]
	v_mov_b32_e32 v148, v8
	v_mov_b32_e32 v149, v6
	v_mov_b32_e32 v6, v9
	v_pk_add_f32 v[6:7], v[148:149], v[6:7]
	v_mov_b32_e32 v148, v140
	v_mov_b32_e32 v149, v142
	v_pk_mul_f32 v[8:9], v[82:83], v[82:83]
	v_pk_mul_f32 v[148:149], v[148:149], v[148:149]
	v_pk_fma_f32 v[8:9], v[84:85], v[84:85], v[8:9]
	s_waitcnt vmcnt(3)
	v_lshlrev_b32_e32 v198, 16, v160
	s_waitcnt vmcnt(2)
	v_lshlrev_b32_e32 v199, 16, v164
	v_lshlrev_b32_e32 v50, 16, v52
	s_waitcnt vmcnt(0)
	v_lshlrev_b32_e32 v144, 16, v68
	v_and_b32_e32 v145, 0xffff0000, v68
	v_lshlrev_b32_e32 v128, 16, v69
	v_and_b32_e32 v129, 0xffff0000, v69
	global_load_dwordx2 v[68:69], v[70:71], off offset:2048
	v_and_b32_e32 v51, 0xffff0000, v52
	v_lshlrev_b32_e32 v55, 16, v53
	v_and_b32_e32 v53, 0xffff0000, v53
	v_add_f32_e32 v52, v66, v67
	v_mov_b32_e32 v3, v50
	v_mov_b32_e32 v5, v51
	v_pk_add_f32 v[2:3], v[2:3], v[4:5]
	v_pk_add_f32 v[4:5], v[54:55], v[52:53]
	v_and_b32_e32 v197, 0xffff0000, v164
	v_pk_add_f32 v[2:3], v[2:3], v[4:5]
	v_and_b32_e32 v196, 0xffff0000, v160
	v_add_f32_e32 v2, v2, v3
	v_lshlrev_b32_e32 v193, 16, v165
	v_lshlrev_b32_e32 v192, 16, v161
	v_add_f32_dpp v2, v2, v2 quad_perm:[1,0,3,2] row_mask:0xf bank_mask:0xf bound_ctrl:1
	v_and_b32_e32 v191, 0xffff0000, v165
	v_and_b32_e32 v190, 0xffff0000, v161
	v_add_f32_dpp v2, v2, v2 quad_perm:[2,3,0,1] row_mask:0xf bank_mask:0xf bound_ctrl:1
	v_pk_add_f32 v[4:5], v[192:193], v[190:191]
	v_lshlrev_b32_e32 v173, 16, v159
	v_add_f32_dpp v2, v2, v2 row_half_mirror row_mask:0xf bank_mask:0xf bound_ctrl:1
	v_lshlrev_b32_e32 v172, 16, v158
	v_and_b32_e32 v171, 0xffff0000, v159
	v_add_f32_dpp v2, v2, v2 row_ror:8 row_mask:0xf bank_mask:0xf bound_ctrl:1
	v_and_b32_e32 v170, 0xffff0000, v158
	v_readlane_b32 s2, v2, 16
	v_readlane_b32 s3, v2, 48
	v_readlane_b32 s0, v2, 0
	v_readlane_b32 s1, v2, 32
	v_mov_b32_e32 v2, s2
	v_mov_b32_e32 v3, s3
	v_pk_add_f32 v[2:3], s[0:1], v[2:3]
	v_add_f32_e32 v102, v144, v145
	v_add_f32_e32 v40, v2, v3
	v_pk_add_f32 v[2:3], v[198:199], v[196:197]
	v_add_f32_e32 v100, v128, v129
	v_pk_add_f32 v[2:3], v[2:3], v[4:5]
	v_mov_b32_e32 v158, v141
	v_add_f32_e32 v2, 0, v2
	v_add_f32_e32 v108, v2, v3
	v_pk_add_f32 v[2:3], v[172:173], v[170:171]
	v_mov_b32_e32 v159, v143
	v_pk_add_f32 v[2:3], v[2:3], v[2:3] op_sel:[0,1] op_sel_hi:[1,0]
	v_pk_fma_f32 v[148:149], v[158:159], v[158:159], v[148:149]
	v_mov_b32_e32 v159, v8
	v_mov_b32_e32 v158, v148
	v_mov_b32_e32 v8, v149
	v_pk_add_f32 v[8:9], v[158:159], v[8:9]
	v_pk_mul_f32 v[148:149], v[58:59], v[58:59]
	v_pk_mul_f32 v[158:159], v[42:43], v[42:43]
	v_pk_fma_f32 v[148:149], v[60:61], v[60:61], v[148:149]
	v_pk_fma_f32 v[158:159], v[44:45], v[44:45], v[158:159]
	v_mov_b32_e32 v161, v148
	v_mov_b32_e32 v160, v158
	v_mov_b32_e32 v148, v159
	v_pk_add_f32 v[148:149], v[160:161], v[148:149]
	v_pk_mul_f32 v[158:159], v[90:91], v[90:91]
	v_mov_b32_e32 v160, v126
	v_mov_b32_e32 v161, v124
	v_pk_fma_f32 v[158:159], v[78:79], v[78:79], v[158:159]
	v_pk_mul_f32 v[160:161], v[160:161], v[160:161]
	v_mov_b32_e32 v164, v127
	v_mov_b32_e32 v165, v125
	v_pk_fma_f32 v[160:161], v[164:165], v[164:165], v[160:161]
	v_pk_mul_f32 v[164:165], v[62:63], v[62:63]
	v_fmac_f32_e32 v182, 0xba000000, v40
	v_pk_fma_f32 v[164:165], v[56:57], v[56:57], v[164:165]
	v_fmac_f32_e32 v194, 0xba000000, v40
	v_fmac_f32_e32 v184, 0xba000000, v40
	v_fmac_f32_e32 v186, 0xba000000, v40
	v_fmac_f32_e32 v183, 0xba000000, v40
	v_fmac_f32_e32 v195, 0xba000000, v40
	v_fmac_f32_e32 v185, 0xba000000, v40
	v_fmac_f32_e32 v187, 0xba000000, v40
	v_fmac_f32_e32 v166, 0xba000000, v40
	v_fmac_f32_e32 v168, 0xba000000, v40
	v_fmac_f32_e32 v167, 0xba000000, v40
	v_fmac_f32_e32 v169, 0xba000000, v40
	v_fmac_f32_e32 v121, 0xba000000, v40
	s_waitcnt vmcnt(0)
	v_lshlrev_b32_e32 v109, 16, v68
	v_and_b32_e32 v107, 0xffff0000, v68
	v_lshlrev_b32_e32 v103, 16, v69
	v_and_b32_e32 v101, 0xffff0000, v69
	global_load_dwordx2 v[174:175], v[70:71], off offset:2560
	global_load_dwordx2 v[68:69], v[70:71], off offset:3072
	v_mov_b32_e32 v3, v107
	global_load_dwordx2 v[70:71], v[70:71], off offset:3584
	v_pk_add_f32 v[2:3], v[108:109], v[2:3]
	v_pk_add_f32 v[4:5], v[102:103], v[100:101]
	v_fmac_f32_e32 v120, 0xba000000, v40
	v_pk_add_f32 v[2:3], v[2:3], v[4:5]
	v_fmac_f32_e32 v99, 0xba000000, v40
	v_pk_add_f32 v[2:3], v[2:3], v[2:3] op_sel:[0,1] op_sel_hi:[1,0]
	v_fmac_f32_e32 v123, 0xba000000, v40
	v_fmac_f32_e32 v122, 0xba000000, v40
	v_fmac_f32_e32 v97, 0xba000000, v40
	v_fmac_f32_e32 v93, 0xba000000, v40
	v_mov_b32_e32 v92, v99
	v_fmac_f32_e32 v134, 0xba000000, v40
	v_fmac_f32_e32 v136, 0xba000000, v40
	v_fmac_f32_e32 v95, 0xba000000, v40
	v_mov_b32_e32 v94, v97
	v_fmac_f32_e32 v135, 0xba000000, v40
	v_fmac_f32_e32 v137, 0xba000000, v40
	v_fmac_f32_e32 v65, 0xba000000, v40
	v_fmac_f32_e32 v64, 0xba000000, v40
	v_fmac_f32_e32 v67, 0xba000000, v40
	v_fmac_f32_e32 v66, 0xba000000, v40
	v_fmac_f32_e32 v55, 0xba000000, v40
	v_fmac_f32_e32 v51, 0xba000000, v40
	v_fmac_f32_e32 v50, 0xba000000, v40
	v_fmac_f32_e32 v53, 0xba000000, v40
	v_mov_b32_e32 v52, v55
	s_waitcnt vmcnt(2)
	v_lshlrev_b32_e32 v133, 16, v175
	v_lshlrev_b32_e32 v132, 16, v174
	v_and_b32_e32 v131, 0xffff0000, v175
	v_and_b32_e32 v130, 0xffff0000, v174
	v_pk_add_f32 v[4:5], v[132:133], v[130:131]
	s_waitcnt vmcnt(1)
	v_lshlrev_b32_e32 v74, 16, v68
	v_and_b32_e32 v75, 0xffff0000, v68
	v_lshlrev_b32_e32 v68, 16, v69
	v_and_b32_e32 v69, 0xffff0000, v69
	s_waitcnt vmcnt(0)
	v_lshlrev_b32_e32 v76, 16, v70
	v_and_b32_e32 v77, 0xffff0000, v70
	v_pk_add_f32 v[4:5], v[4:5], v[4:5] op_sel:[0,1] op_sel_hi:[1,0]
	v_lshlrev_b32_e32 v73, 16, v71
	v_and_b32_e32 v71, 0xffff0000, v71
	v_add_f32_e32 v72, v74, v75
	v_add_f32_e32 v70, v68, v69
	v_mov_b32_e32 v3, v76
	v_mov_b32_e32 v5, v77
	v_pk_add_f32 v[2:3], v[2:3], v[4:5]
	v_pk_add_f32 v[4:5], v[72:73], v[70:71]
	v_pk_mul_f32 v[174:175], v[48:49], v[48:49]
	v_pk_add_f32 v[2:3], v[2:3], v[4:5]
	v_pk_mul_f32 v[4:5], v[178:179], v[178:179]
	v_add_f32_e32 v2, v2, v3
	v_pk_fma_f32 v[4:5], v[180:181], v[180:181], v[4:5]
	v_pk_fma_f32 v[174:175], v[38:39], v[38:39], v[174:175]
	v_add_f32_dpp v2, v2, v2 quad_perm:[1,0,3,2] row_mask:0xf bank_mask:0xf bound_ctrl:1
	v_add_f32_e32 v0, v4, v5
	v_mov_b32_e32 v4, v201
	v_add_f32_dpp v2, v2, v2 quad_perm:[2,3,0,1] row_mask:0xf bank_mask:0xf bound_ctrl:1
	v_mov_b32_e32 v5, v189
	v_pk_mul_f32 v[4:5], v[4:5], v[4:5]
	v_add_f32_dpp v2, v2, v2 row_half_mirror row_mask:0xf bank_mask:0xf bound_ctrl:1
	s_nop 1
	v_add_f32_dpp v2, v2, v2 row_ror:8 row_mask:0xf bank_mask:0xf bound_ctrl:1
	s_nop 0
	v_readlane_b32 s2, v2, 16
	v_readlane_b32 s3, v2, 48
	v_readlane_b32 s0, v2, 0
	v_readlane_b32 s1, v2, 32
	v_mov_b32_e32 v2, s2
	v_mov_b32_e32 v3, s3
	v_pk_add_f32 v[2:3], s[0:1], v[2:3]
	s_nop 0
	v_add_f32_e32 v46, v2, v3
	v_pk_mul_f32 v[2:3], v[10:11], v[10:11]
	v_fmac_f32_e32 v196, 0xba000000, v46
	v_pk_fma_f32 v[2:3], v[12:13], v[12:13], v[2:3]
	v_fmac_f32_e32 v198, 0xba000000, v46
	v_add_f32_e32 v2, v2, v3
	v_add_f32_e32 v0, v2, v0
	v_add_f32_e32 v0, v7, v0
	v_add_f32_e32 v0, v6, v0
	v_add_f32_e32 v0, v9, v0
	v_add_f32_e32 v0, v8, v0
	v_add_f32_e32 v0, v149, v0
	v_add_f32_e32 v0, v148, v0
	v_mov_b32_e32 v148, v150
	v_mov_b32_e32 v149, v176
	v_add_f32_dpp v0, v0, v0 quad_perm:[1,0,3,2] row_mask:0xf bank_mask:0xf bound_ctrl:1
	v_mov_b32_e32 v176, v151
	v_mov_b32_e32 v6, v154
	v_add_f32_dpp v0, v0, v0 quad_perm:[2,3,0,1] row_mask:0xf bank_mask:0xf bound_ctrl:1
	v_mov_b32_e32 v7, v152
	v_pk_fma_f32 v[4:5], v[176:177], v[176:177], v[4:5]
	v_add_f32_dpp v0, v0, v0 row_half_mirror row_mask:0xf bank_mask:0xf bound_ctrl:1
	v_pk_mul_f32 v[6:7], v[6:7], v[6:7]
	v_mov_b32_e32 v8, v155
	v_add_f32_dpp v0, v0, v0 row_ror:8 row_mask:0xf bank_mask:0xf bound_ctrl:1
	v_mov_b32_e32 v9, v153
	v_readlane_b32 s2, v0, 16
	v_readlane_b32 s3, v0, 48
	v_readlane_b32 s0, v0, 0
	v_readlane_b32 s1, v0, 32
	v_mov_b32_e32 v2, s2
	v_mov_b32_e32 v3, s3
	v_pk_add_f32 v[2:3], s[0:1], v[2:3]
	v_pk_fma_f32 v[6:7], v[8:9], v[8:9], v[6:7]
	v_add_f32_e32 v0, v2, v3
	v_mov_b32_e32 v2, v200
	v_mov_b32_e32 v3, v188
	v_pk_mul_f32 v[2:3], v[2:3], v[2:3]
	v_fmamk_f32 v0, v0, 0x3a000000, v203
	v_pk_fma_f32 v[2:3], v[148:149], v[148:149], v[2:3]
	v_rsq_f32_e32 v116, v0
	v_pk_mul_f32 v[8:9], v[118:119], v[118:119]
	v_add_f32_e32 v0, v4, v5
	v_add_f32_e32 v2, v2, v3
	v_pk_fma_f32 v[8:9], v[114:115], v[114:115], v[8:9]
	v_add_f32_e32 v0, v2, v0
	v_add_f32_e32 v2, v6, v7
	v_add_f32_e32 v0, v2, v0
	v_add_f32_e32 v2, v8, v9
	v_add_f32_e32 v0, v2, v0
	v_add_f32_e32 v2, v158, v159
	v_add_f32_e32 v0, v2, v0
	v_add_f32_e32 v2, v160, v161
	v_add_f32_e32 v0, v2, v0
	v_add_f32_e32 v2, v164, v165
	v_add_f32_e32 v0, v2, v0
	v_add_f32_e32 v2, v174, v175
	v_add_f32_e32 v0, v2, v0
	v_mov_b32_e32 v2, v194
	v_mov_b32_e32 v3, v182
	v_pk_mul_f32 v[2:3], v[2:3], v[2:3]
	v_mov_b32_e32 v4, v186
	v_mov_b32_e32 v5, v184
	v_add_f32_dpp v0, v0, v0 quad_perm:[1,0,3,2] row_mask:0xf bank_mask:0xf bound_ctrl:1
	v_pk_fma_f32 v[2:3], v[4:5], v[4:5], v[2:3]
	v_mov_b32_e32 v4, v195
	v_mov_b32_e32 v5, v183
	v_add_f32_dpp v0, v0, v0 quad_perm:[2,3,0,1] row_mask:0xf bank_mask:0xf bound_ctrl:1
	v_pk_mul_f32 v[4:5], v[4:5], v[4:5]
	v_mov_b32_e32 v6, v187
	v_mov_b32_e32 v7, v185
	v_add_f32_dpp v0, v0, v0 row_half_mirror row_mask:0xf bank_mask:0xf bound_ctrl:1
	v_pk_fma_f32 v[4:5], v[6:7], v[6:7], v[4:5]
	v_mov_b32_e32 v6, v168
	v_mov_b32_e32 v7, v166
	v_add_f32_dpp v0, v0, v0 row_ror:8 row_mask:0xf bank_mask:0xf bound_ctrl:1
	v_pk_mul_f32 v[6:7], v[6:7], v[6:7]
	v_mov_b32_e32 v8, v169
	v_mov_b32_e32 v9, v167
	v_readlane_b32 s0, v0, 0
	v_readlane_b32 s4, v0, 16
	v_readlane_b32 s1, v0, 32
	v_readlane_b32 s5, v0, 48
	v_pk_fma_f32 v[6:7], v[8:9], v[8:9], v[6:7]
	v_pk_mul_f32 v[8:9], v[120:121], v[120:121]
	v_add_f32_e32 v0, v4, v5
	v_add_f32_e32 v2, v2, v3
	v_pk_fma_f32 v[8:9], v[122:123], v[122:123], v[8:9]
	v_pk_mul_f32 v[158:159], v[92:93], v[92:93]
	v_mov_b32_e32 v160, v136
	v_mov_b32_e32 v161, v134
	v_add_f32_e32 v0, v2, v0
	v_add_f32_e32 v2, v6, v7
	v_pk_fma_f32 v[158:159], v[94:95], v[94:95], v[158:159]
	v_pk_mul_f32 v[160:161], v[160:161], v[160:161]
	v_mov_b32_e32 v164, v137
	v_mov_b32_e32 v165, v135
	v_add_f32_e32 v0, v2, v0
	v_add_f32_e32 v2, v8, v9
	v_pk_fma_f32 v[160:161], v[164:165], v[164:165], v[160:161]
	v_pk_mul_f32 v[164:165], v[64:65], v[64:65]
	v_add_f32_e32 v0, v2, v0
	v_add_f32_e32 v2, v158, v159
	v_pk_fma_f32 v[164:165], v[66:67], v[66:67], v[164:165]
	v_pk_mul_f32 v[174:175], v[50:51], v[50:51]
	v_add_f32_e32 v0, v2, v0
	v_add_f32_e32 v2, v160, v161
	v_pk_fma_f32 v[174:175], v[52:53], v[52:53], v[174:175]
	v_add_f32_e32 v0, v2, v0
	v_add_f32_e32 v2, v164, v165
	v_add_f32_e32 v0, v2, v0
	v_add_f32_e32 v2, v174, v175
	v_add_f32_e32 v0, v2, v0
	v_fmac_f32_e32 v190, 0xba000000, v46
	v_fmac_f32_e32 v192, 0xba000000, v46
	v_mov_b32_e32 v2, v198
	v_mov_b32_e32 v3, v196
	v_pk_mul_f32 v[2:3], v[2:3], v[2:3]
	v_mov_b32_e32 v4, v192
	v_mov_b32_e32 v5, v190
	v_fmac_f32_e32 v197, 0xba000000, v46
	v_fmac_f32_e32 v199, 0xba000000, v46
	v_add_f32_dpp v0, v0, v0 quad_perm:[1,0,3,2] row_mask:0xf bank_mask:0xf bound_ctrl:1
	v_pk_fma_f32 v[2:3], v[4:5], v[4:5], v[2:3]
	v_fmac_f32_e32 v191, 0xba000000, v46
	v_fmac_f32_e32 v193, 0xba000000, v46
	v_mov_b32_e32 v4, v199
	v_mov_b32_e32 v5, v197
	v_add_f32_dpp v0, v0, v0 quad_perm:[2,3,0,1] row_mask:0xf bank_mask:0xf bound_ctrl:1
	v_pk_mul_f32 v[4:5], v[4:5], v[4:5]
	v_mov_b32_e32 v6, v193
	v_mov_b32_e32 v7, v191
	v_fmac_f32_e32 v170, 0xba000000, v46
	v_fmac_f32_e32 v172, 0xba000000, v46
	v_add_f32_dpp v0, v0, v0 row_half_mirror row_mask:0xf bank_mask:0xf bound_ctrl:1
	v_pk_fma_f32 v[4:5], v[6:7], v[6:7], v[4:5]
	v_fmac_f32_e32 v171, 0xba000000, v46
	v_fmac_f32_e32 v173, 0xba000000, v46
	v_mov_b32_e32 v6, v172
	v_mov_b32_e32 v7, v170
	v_add_f32_dpp v0, v0, v0 row_ror:8 row_mask:0xf bank_mask:0xf bound_ctrl:1
	v_pk_mul_f32 v[6:7], v[6:7], v[6:7]
	v_mov_b32_e32 v8, v173
	v_mov_b32_e32 v9, v171
	v_fmac_f32_e32 v145, 0xba000000, v46
	v_fmac_f32_e32 v144, 0xba000000, v46
	v_fmac_f32_e32 v109, 0xba000000, v46
	v_readlane_b32 s18, v0, 0
	v_readlane_b32 s26, v0, 16
	v_readlane_b32 s19, v0, 32
	v_readlane_b32 s27, v0, 48
	v_pk_fma_f32 v[6:7], v[8:9], v[8:9], v[6:7]
	v_fmac_f32_e32 v129, 0xba000000, v46
	v_fmac_f32_e32 v128, 0xba000000, v46
	v_pk_mul_f32 v[8:9], v[144:145], v[144:145]
	v_fmac_f32_e32 v103, 0xba000000, v46
	v_fmac_f32_e32 v107, 0xba000000, v46
	v_mov_b32_e32 v106, v109
	v_fmac_f32_e32 v130, 0xba000000, v46
	v_fmac_f32_e32 v132, 0xba000000, v46
	v_add_f32_e32 v0, v4, v5
	v_add_f32_e32 v2, v2, v3
	v_pk_fma_f32 v[8:9], v[128:129], v[128:129], v[8:9]
	v_fmac_f32_e32 v101, 0xba000000, v46
	v_pk_mul_f32 v[158:159], v[106:107], v[106:107]
	v_mov_b32_e32 v100, v103
	v_fmac_f32_e32 v131, 0xba000000, v46
	v_fmac_f32_e32 v133, 0xba000000, v46
	v_mov_b32_e32 v160, v132
	v_mov_b32_e32 v161, v130
	v_add_f32_e32 v0, v2, v0
	v_add_f32_e32 v2, v6, v7
	v_pk_fma_f32 v[158:159], v[100:101], v[100:101], v[158:159]
	v_pk_mul_f32 v[160:161], v[160:161], v[160:161]
	v_mov_b32_e32 v164, v133
	v_mov_b32_e32 v165, v131
	v_fmac_f32_e32 v75, 0xba000000, v46
	v_fmac_f32_e32 v74, 0xba000000, v46
	v_add_f32_e32 v0, v2, v0
	v_add_f32_e32 v2, v8, v9
	v_pk_fma_f32 v[160:161], v[164:165], v[164:165], v[160:161]
	v_fmac_f32_e32 v69, 0xba000000, v46
	v_fmac_f32_e32 v68, 0xba000000, v46
	v_pk_mul_f32 v[164:165], v[74:75], v[74:75]
	v_fmac_f32_e32 v73, 0xba000000, v46
	v_fmac_f32_e32 v77, 0xba000000, v46
	v_fmac_f32_e32 v76, 0xba000000, v46
	v_add_f32_e32 v0, v2, v0
	v_add_f32_e32 v2, v158, v159
	v_pk_fma_f32 v[164:165], v[68:69], v[68:69], v[164:165]
	v_fmac_f32_e32 v71, 0xba000000, v46
	v_pk_mul_f32 v[174:175], v[76:77], v[76:77]
	v_mov_b32_e32 v70, v73
	v_add_f32_e32 v0, v2, v0
	v_add_f32_e32 v2, v160, v161
	v_pk_fma_f32 v[174:175], v[70:71], v[70:71], v[174:175]
	v_add_f32_e32 v0, v2, v0
	v_add_f32_e32 v2, v164, v165
	v_add_f32_e32 v0, v2, v0
	v_add_f32_e32 v2, v174, v175
	v_add_f32_e32 v0, v2, v0
	global_load_dwordx4 v[2:5], v[16:17], off
	global_load_dwordx4 v[6:9], v[18:19], off
	v_add_f32_dpp v0, v0, v0 quad_perm:[1,0,3,2] row_mask:0xf bank_mask:0xf bound_ctrl:1
	v_pk_mul_f32 v[10:11], v[10:11], v[116:117] op_sel_hi:[1,0]
	v_pk_mul_f32 v[12:13], v[12:13], v[116:117] op_sel_hi:[1,0]
	v_add_f32_dpp v0, v0, v0 quad_perm:[2,3,0,1] row_mask:0xf bank_mask:0xf bound_ctrl:1
	v_lshl_add_u64 v[174:175], s[54:55], 0, v[14:15]
	s_waitcnt vmcnt(0)
	v_pk_fma_f32 v[12:13], v[12:13], v[4:5], v[8:9]
	v_add_f32_dpp v0, v0, v0 row_half_mirror row_mask:0xf bank_mask:0xf bound_ctrl:1
	v_pk_fma_f32 v[10:11], v[10:11], v[2:3], v[6:7]
	global_store_dwordx4 v[174:175], v[10:13], off
	v_add_f32_dpp v0, v0, v0 row_ror:8 row_mask:0xf bank_mask:0xf bound_ctrl:1
	s_nop 0
	v_readlane_b32 s29, v0, 0
	v_readlane_b32 s39, v0, 16
	v_readlane_b32 s38, v0, 32
	v_readlane_b32 s44, v0, 48
	v_cndmask_b32_e64 v0, 0, 1, s[22:23]
	v_cmp_ne_u32_e64 s[2:3], 1, v0
	v_lshlrev_b32_e32 v0, 3, v138
	s_cbranch_vccnz .LBB0_157
	v_bfe_u32 v38, v10, 16, 1
	v_add3_u32 v10, v10, v38, s60
	v_bfe_u32 v38, v11, 16, 1
	v_lshrrev_b32_e32 v10, 16, v10
	v_add3_u32 v11, v11, v38, s60
	v_and_or_b32 v10, v11, s33, v10
	v_bfe_u32 v11, v12, 16, 1
	v_add3_u32 v11, v12, v11, s60
	v_bfe_u32 v12, v13, 16, 1
	v_lshrrev_b32_e32 v11, 16, v11
	v_add3_u32 v12, v13, v12, s60
	v_and_or_b32 v11, v12, s33, v11
	global_store_dwordx2 v0, v[10:11], s[66:67]
